# v50 plus LDS-DMA issue in the attention loop without M0 save and restore (M0 written directly, 36 fewer scalar instructions per six tiles)
# speedup vs baseline: 1.0034x; 1.0016x over previous
.LBB0_618:
	ds_read_b64_tr_b16 v[52:53], v199 offset:24576
	ds_read_b64_tr_b16 v[54:55], v199 offset:25088
	v_mfma_f32_32x32x16_bf16 v[114:129], v[190:193], v[150:153], v[34:49]
	v_add_f32_e32 v50, v82, v50
	v_add_f32_e32 v194, v83, v194
	v_add_f32_e32 v195, v84, v195
	v_add_f32_e32 v196, v85, v196
	v_add_f32_e32 v50, v86, v50
	v_add_f32_e32 v194, v87, v194
	v_cvt_pk_bf16_f32 v158, v82, v83
	v_cvt_pk_bf16_f32 v159, v84, v85
	ds_read_b64_tr_b16 v[60:61], v199 offset:28672
	ds_read_b64_tr_b16 v[62:63], v199 offset:29184
	v_mfma_f32_32x32x16_bf16 v[98:113], v[186:189], v[150:153], v[34:49]
	v_add_f32_e32 v195, v88, v195
	v_add_f32_e32 v196, v89, v196
	v_add_f32_e32 v50, v90, v50
	v_add_f32_e32 v194, v91, v194
	v_cvt_pk_bf16_f32 v160, v86, v87
	v_cvt_pk_bf16_f32 v161, v88, v89
	ds_read_b64_tr_b16 v[82:83], v199 offset:25600
	ds_read_b64_tr_b16 v[84:85], v199 offset:26112
	v_mfma_f32_32x32x16_bf16 v[114:129], v[182:185], v[138:141], v[114:129]
	v_add_f32_e32 v195, v92, v195
	v_add_f32_e32 v196, v93, v196
	v_add_f32_e32 v50, v94, v50
	v_add_f32_e32 v194, v95, v194
	v_cvt_pk_bf16_f32 v154, v90, v91
	v_cvt_pk_bf16_f32 v155, v92, v93
	ds_read_b64_tr_b16 v[86:87], v199 offset:29696
	ds_read_b64_tr_b16 v[88:89], v199 offset:30208
	v_mfma_f32_32x32x16_bf16 v[98:113], v[178:181], v[138:141], v[98:113]
	v_add_f32_e32 v195, v96, v195
	v_add_f32_e32 v196, v97, v196
	v_add_f32_e32 v50, v66, v50
	v_add_f32_e32 v194, v67, v194
	v_cvt_pk_bf16_f32 v156, v94, v95
	v_cvt_pk_bf16_f32 v157, v96, v97
	ds_read_b64_tr_b16 v[90:91], v199 offset:26624
	ds_read_b64_tr_b16 v[92:93], v199 offset:27136
	v_mfma_f32_32x32x16_bf16 v[114:129], v[174:177], v[134:137], v[114:129]
	v_add_f32_e32 v195, v68, v195
	v_add_f32_e32 v196, v69, v196
	v_add_f32_e32 v50, v70, v50
	v_add_f32_e32 v194, v71, v194
	v_cvt_pk_bf16_f32 v146, v66, v67
	v_cvt_pk_bf16_f32 v147, v68, v69
	ds_read_b64_tr_b16 v[64:65], v199 offset:30720
	ds_read_b64_tr_b16 v[66:67], v199 offset:31232
	v_mfma_f32_32x32x16_bf16 v[98:113], v[170:173], v[134:137], v[98:113]
	v_add_f32_e32 v195, v72, v195
	v_add_f32_e32 v196, v73, v196
	v_add_f32_e32 v50, v74, v50
	v_add_f32_e32 v194, v75, v194
	v_cvt_pk_bf16_f32 v148, v70, v71
	v_cvt_pk_bf16_f32 v149, v72, v73
	ds_read_b64_tr_b16 v[68:69], v199 offset:27648
	ds_read_b64_tr_b16 v[70:71], v199 offset:28160
	v_mfma_f32_32x32x16_bf16 v[114:129], v[166:169], v[130:133], v[114:129]
	v_add_f32_e32 v195, v76, v195
	v_add_f32_e32 v196, v77, v196
	v_add_f32_e32 v50, v78, v50
	v_add_f32_e32 v194, v79, v194
	v_cvt_pk_bf16_f32 v142, v74, v75
	v_cvt_pk_bf16_f32 v143, v76, v77
	ds_read_b64_tr_b16 v[72:73], v199 offset:31744
	ds_read_b64_tr_b16 v[74:75], v199 offset:32256
	v_mfma_f32_32x32x16_bf16 v[98:113], v[162:165], v[130:133], v[98:113]
	v_add_f32_e32 v195, v80, v195
	v_add_f32_e32 v196, v81, v196
	v_cvt_pk_bf16_f32 v144, v78, v79
	v_cvt_pk_bf16_f32 v145, v80, v81
	s_add_i32 m0, s31, s70
	s_nop 0
	global_load_lds_dwordx4 v197, s[98:99]
	s_add_i32 m0, s76, s71
	s_nop 0
	global_load_lds_dwordx4 v197, s[100:101]
	s_add_u32 s98, s98, 0x2000
	s_addc_u32 s99, s99, 0
	s_add_u32 s100, s100, 0x2000
	s_addc_u32 s101, s101, 0
	s_waitcnt lgkmcnt(14)
	v_mfma_f32_32x32x16_bf16 v[2:17], v[158:161], v[52:55], v[2:17]
	v_exp_f32_e32 v114, v114
	v_exp_f32_e32 v115, v115
	v_exp_f32_e32 v116, v116
	v_exp_f32_e32 v117, v117
	s_waitcnt lgkmcnt(12)
	v_mfma_f32_32x32x16_bf16 v[18:33], v[158:161], v[60:63], v[18:33]
	v_exp_f32_e32 v118, v118
	v_exp_f32_e32 v119, v119
	v_exp_f32_e32 v120, v120
	v_exp_f32_e32 v121, v121
	ds_read_b128 v[60:63], v204
	ds_read_b128 v[162:165], v204 offset:512
	s_waitcnt lgkmcnt(12)
	v_mfma_f32_32x32x16_bf16 v[2:17], v[154:157], v[82:85], v[2:17]
	v_exp_f32_e32 v122, v122
	v_exp_f32_e32 v123, v123
	v_exp_f32_e32 v124, v124
	v_exp_f32_e32 v125, v125
	ds_read_b128 v[166:169], v204 offset:2048
	ds_read_b128 v[170:173], v204 offset:2560
	s_waitcnt lgkmcnt(12)
	v_mfma_f32_32x32x16_bf16 v[18:33], v[154:157], v[86:89], v[18:33]
	v_exp_f32_e32 v126, v126
	v_exp_f32_e32 v127, v127
	v_exp_f32_e32 v128, v128
	v_exp_f32_e32 v129, v129
	ds_read_b128 v[174:177], v204 offset:4096
	ds_read_b128 v[178:181], v204 offset:4608
	s_waitcnt lgkmcnt(12)
	v_mfma_f32_32x32x16_bf16 v[2:17], v[146:149], v[90:93], v[2:17]
	v_exp_f32_e32 v98, v98
	v_exp_f32_e32 v99, v99
	v_exp_f32_e32 v100, v100
	v_exp_f32_e32 v101, v101
	ds_read_b128 v[182:185], v204 offset:6144
	ds_read_b128 v[52:55], v204 offset:6656
	s_waitcnt lgkmcnt(12)
	v_mfma_f32_32x32x16_bf16 v[18:33], v[146:149], v[64:67], v[18:33]
	v_exp_f32_e32 v102, v102
	v_exp_f32_e32 v103, v103
	v_exp_f32_e32 v104, v104
	v_exp_f32_e32 v105, v105
	s_waitcnt lgkmcnt(10)
	v_mfma_f32_32x32x16_bf16 v[2:17], v[142:145], v[68:71], v[2:17]
	v_exp_f32_e32 v106, v106
	v_exp_f32_e32 v107, v107
	v_exp_f32_e32 v108, v108
	v_exp_f32_e32 v109, v109
	s_waitcnt lgkmcnt(8)
	v_mfma_f32_32x32x16_bf16 v[18:33], v[142:145], v[72:75], v[18:33]
	v_exp_f32_e32 v110, v110
	v_exp_f32_e32 v111, v111
	v_exp_f32_e32 v112, v112
	v_exp_f32_e32 v113, v113
	s_add_i32 s6, s76, 0x2000
	s_cmpk_lg_i32 s76, 0x4000
	s_cselect_b32 s31, s6, 0
	s_waitcnt vmcnt(2) lgkmcnt(0)
	s_barrier
; #define WAIT_BAR(N) asm volatile("s_waitcnt vmcnt(" #N ") lgkmcnt(0)\n\ts_barrier":::"memory")
;   #define RESC() do{ if(resc){ asm volatile("s_waitcnt lgkmcnt(0)":::"memory"); \
;       _Pragma("unroll") for(int d_=0;d_<2;++d_) _Pragma("unroll") for(int r=0;r<16;++r)o[d_][r]*=wsf[crow(r,hi)]; } }while(0)
;   #define ROT() do{sl_prev=sl_cur;sl_cur=sl_next;sl_next=(sl_next==(NSLOT-1)*SLOTB)?0:sl_next+SLOTB;}while(0)
; template<int THRL> __device__ __forceinline__ void attn_unit(const bf16*Qu,const bf16*__restrict__ Kh,const bf16*__restrict__ Vh,bf16*Ou,const int NT,const float shift,char*shm){
;     ...
;     STEP(pB0,pB1,pA0,pA1,t,true,true,true);     WAIT_BAR(2); RESC(); ROT();
;     STEP(pA0,pA1,pB0,pB1,t+1,true,true,true);   WAIT_BAR(2); RESC(); ROT();
	ds_read_b64_tr_b16 v[186:187], v200 offset:24576
	ds_read_b64_tr_b16 v[188:189], v200 offset:25088
	v_mfma_f32_32x32x16_bf16 v[82:97], v[60:63], v[150:153], v[34:49]
	v_add_f32_e32 v50, v114, v50
	v_add_f32_e32 v194, v115, v194
	v_add_f32_e32 v195, v116, v195
	v_add_f32_e32 v196, v117, v196
	v_add_f32_e32 v50, v118, v50
	v_add_f32_e32 v194, v119, v194
	v_cvt_pk_bf16_f32 v158, v114, v115
	v_cvt_pk_bf16_f32 v159, v116, v117
	ds_read_b64_tr_b16 v[60:61], v200 offset:28672
	ds_read_b64_tr_b16 v[62:63], v200 offset:29184
	v_mfma_f32_32x32x16_bf16 v[66:81], v[162:165], v[150:153], v[34:49]
	v_add_f32_e32 v195, v120, v195
	v_add_f32_e32 v196, v121, v196
	v_add_f32_e32 v50, v122, v50
	v_add_f32_e32 v194, v123, v194
	v_cvt_pk_bf16_f32 v160, v118, v119
	v_cvt_pk_bf16_f32 v161, v120, v121
	ds_read_b64_tr_b16 v[114:115], v200 offset:25600
	ds_read_b64_tr_b16 v[116:117], v200 offset:26112
	v_mfma_f32_32x32x16_bf16 v[82:97], v[166:169], v[138:141], v[82:97]
	v_add_f32_e32 v195, v124, v195
	v_add_f32_e32 v196, v125, v196
	v_add_f32_e32 v50, v126, v50
	v_add_f32_e32 v194, v127, v194
	v_cvt_pk_bf16_f32 v154, v122, v123
	v_cvt_pk_bf16_f32 v155, v124, v125
	ds_read_b64_tr_b16 v[118:119], v200 offset:29696
	ds_read_b64_tr_b16 v[120:121], v200 offset:30208
	v_mfma_f32_32x32x16_bf16 v[66:81], v[170:173], v[138:141], v[66:81]
	v_add_f32_e32 v195, v128, v195
	v_add_f32_e32 v196, v129, v196
	v_add_f32_e32 v50, v98, v50
	v_add_f32_e32 v194, v99, v194
	v_cvt_pk_bf16_f32 v156, v126, v127
	v_cvt_pk_bf16_f32 v157, v128, v129
	ds_read_b64_tr_b16 v[122:123], v200 offset:26624
	ds_read_b64_tr_b16 v[124:125], v200 offset:27136
	v_mfma_f32_32x32x16_bf16 v[82:97], v[174:177], v[134:137], v[82:97]
	v_add_f32_e32 v195, v100, v195
	v_add_f32_e32 v196, v101, v196
	v_add_f32_e32 v50, v102, v50
	v_add_f32_e32 v194, v103, v194
	v_cvt_pk_bf16_f32 v146, v98, v99
	v_cvt_pk_bf16_f32 v147, v100, v101
	ds_read_b64_tr_b16 v[98:99], v200 offset:30720
	ds_read_b64_tr_b16 v[100:101], v200 offset:31232
	v_mfma_f32_32x32x16_bf16 v[66:81], v[178:181], v[134:137], v[66:81]
	v_add_f32_e32 v195, v104, v195
	v_add_f32_e32 v196, v105, v196
	v_add_f32_e32 v50, v106, v50
	v_add_f32_e32 v194, v107, v194
	v_cvt_pk_bf16_f32 v148, v102, v103
	v_cvt_pk_bf16_f32 v149, v104, v105
	ds_read_b64_tr_b16 v[102:103], v200 offset:27648
	ds_read_b64_tr_b16 v[104:105], v200 offset:28160
	v_mfma_f32_32x32x16_bf16 v[82:97], v[182:185], v[130:133], v[82:97]
	v_add_f32_e32 v195, v108, v195
	v_add_f32_e32 v196, v109, v196
	v_add_f32_e32 v50, v110, v50
	v_add_f32_e32 v194, v111, v194
	v_cvt_pk_bf16_f32 v142, v106, v107
	v_cvt_pk_bf16_f32 v143, v108, v109
	ds_read_b64_tr_b16 v[106:107], v200 offset:31744
	ds_read_b64_tr_b16 v[108:109], v200 offset:32256
	v_mfma_f32_32x32x16_bf16 v[66:81], v[52:55], v[130:133], v[66:81]
	v_add_f32_e32 v195, v112, v195
	v_add_f32_e32 v196, v113, v196
	v_cvt_pk_bf16_f32 v144, v110, v111
	v_cvt_pk_bf16_f32 v145, v112, v113
	s_add_i32 m0, s76, s70
	s_nop 0
	global_load_lds_dwordx4 v197, s[98:99]
	s_add_i32 m0, s31, s71
	s_nop 0
	global_load_lds_dwordx4 v197, s[100:101]
	s_add_u32 s98, s98, 0x2000
	s_addc_u32 s99, s99, 0
	s_add_u32 s100, s100, 0x2000
	s_addc_u32 s101, s101, 0
	s_waitcnt lgkmcnt(14)
	v_mfma_f32_32x32x16_bf16 v[2:17], v[158:161], v[186:189], v[2:17]
	v_exp_f32_e32 v82, v82
	v_exp_f32_e32 v83, v83
	v_exp_f32_e32 v84, v84
	v_exp_f32_e32 v85, v85
	s_waitcnt lgkmcnt(12)
	v_mfma_f32_32x32x16_bf16 v[18:33], v[158:161], v[60:63], v[18:33]
	v_exp_f32_e32 v86, v86
	v_exp_f32_e32 v87, v87
	v_exp_f32_e32 v88, v88
	v_exp_f32_e32 v89, v89
	ds_read_b128 v[190:193], v202
	ds_read_b128 v[186:189], v202 offset:512
	s_waitcnt lgkmcnt(12)
	v_mfma_f32_32x32x16_bf16 v[2:17], v[154:157], v[114:117], v[2:17]
	v_exp_f32_e32 v90, v90
	v_exp_f32_e32 v91, v91
	v_exp_f32_e32 v92, v92
	v_exp_f32_e32 v93, v93
	ds_read_b128 v[182:185], v202 offset:2048
	ds_read_b128 v[178:181], v202 offset:2560
	s_waitcnt lgkmcnt(12)
	v_mfma_f32_32x32x16_bf16 v[18:33], v[154:157], v[118:121], v[18:33]
	v_exp_f32_e32 v94, v94
	v_exp_f32_e32 v95, v95
	v_exp_f32_e32 v96, v96
	v_exp_f32_e32 v97, v97
	ds_read_b128 v[174:177], v202 offset:4096
	ds_read_b128 v[170:173], v202 offset:4608
	s_waitcnt lgkmcnt(12)
	v_mfma_f32_32x32x16_bf16 v[2:17], v[146:149], v[122:125], v[2:17]
	v_exp_f32_e32 v66, v66
	v_exp_f32_e32 v67, v67
	v_exp_f32_e32 v68, v68
	v_exp_f32_e32 v69, v69
	ds_read_b128 v[166:169], v202 offset:6144
	ds_read_b128 v[162:165], v202 offset:6656
	s_waitcnt lgkmcnt(12)
	v_mfma_f32_32x32x16_bf16 v[18:33], v[146:149], v[98:101], v[18:33]
	v_exp_f32_e32 v70, v70
	v_exp_f32_e32 v71, v71
	v_exp_f32_e32 v72, v72
	v_exp_f32_e32 v73, v73
	s_waitcnt lgkmcnt(10)
	v_mfma_f32_32x32x16_bf16 v[2:17], v[142:145], v[102:105], v[2:17]
	v_exp_f32_e32 v74, v74
	v_exp_f32_e32 v75, v75
	v_exp_f32_e32 v76, v76
	v_exp_f32_e32 v77, v77
	s_waitcnt lgkmcnt(8)
	v_mfma_f32_32x32x16_bf16 v[18:33], v[142:145], v[106:109], v[18:33]
	v_exp_f32_e32 v78, v78
	v_exp_f32_e32 v79, v79
	v_exp_f32_e32 v80, v80
	v_exp_f32_e32 v81, v81
	s_add_i32 s6, s31, 0x2000
	s_cmpk_lg_i32 s31, 0x4000
	s_mov_b32 s24, s76
	s_cselect_b32 s76, s6, 0
	s_add_i32 s26, s26, 2
	s_cmp_gt_i32 s26, s91
	s_cbranch_scc1 .Lattn_exit
	s_waitcnt vmcnt(2) lgkmcnt(0)
	s_barrier
.Lattn_cpB:
	ds_read_b64_tr_b16 v[52:53], v201 offset:24576
	ds_read_b64_tr_b16 v[54:55], v201 offset:25088
	v_mfma_f32_32x32x16_bf16 v[114:129], v[190:193], v[150:153], v[34:49]
	v_add_f32_e32 v50, v82, v50
	v_add_f32_e32 v194, v83, v194
	v_add_f32_e32 v195, v84, v195
	v_add_f32_e32 v196, v85, v196
	v_add_f32_e32 v50, v86, v50
	v_add_f32_e32 v194, v87, v194
	v_cvt_pk_bf16_f32 v158, v82, v83
	v_cvt_pk_bf16_f32 v159, v84, v85
	ds_read_b64_tr_b16 v[60:61], v201 offset:28672
	ds_read_b64_tr_b16 v[62:63], v201 offset:29184
	v_mfma_f32_32x32x16_bf16 v[98:113], v[186:189], v[150:153], v[34:49]
	v_add_f32_e32 v195, v88, v195
	v_add_f32_e32 v196, v89, v196
	v_add_f32_e32 v50, v90, v50
	v_add_f32_e32 v194, v91, v194
	v_cvt_pk_bf16_f32 v160, v86, v87
	v_cvt_pk_bf16_f32 v161, v88, v89
	ds_read_b64_tr_b16 v[82:83], v201 offset:25600
	ds_read_b64_tr_b16 v[84:85], v201 offset:26112
	v_mfma_f32_32x32x16_bf16 v[114:129], v[182:185], v[138:141], v[114:129]
	v_add_f32_e32 v195, v92, v195
	v_add_f32_e32 v196, v93, v196
	v_add_f32_e32 v50, v94, v50
	v_add_f32_e32 v194, v95, v194
	v_cvt_pk_bf16_f32 v154, v90, v91
	v_cvt_pk_bf16_f32 v155, v92, v93
	ds_read_b64_tr_b16 v[86:87], v201 offset:29696
	ds_read_b64_tr_b16 v[88:89], v201 offset:30208
	v_mfma_f32_32x32x16_bf16 v[98:113], v[178:181], v[138:141], v[98:113]
	v_add_f32_e32 v195, v96, v195
	v_add_f32_e32 v196, v97, v196
	v_add_f32_e32 v50, v66, v50
	v_add_f32_e32 v194, v67, v194
	v_cvt_pk_bf16_f32 v156, v94, v95
	v_cvt_pk_bf16_f32 v157, v96, v97
	ds_read_b64_tr_b16 v[90:91], v201 offset:26624
	ds_read_b64_tr_b16 v[92:93], v201 offset:27136
	v_mfma_f32_32x32x16_bf16 v[114:129], v[174:177], v[134:137], v[114:129]
	v_add_f32_e32 v195, v68, v195
	v_add_f32_e32 v196, v69, v196
	v_add_f32_e32 v50, v70, v50
	v_add_f32_e32 v194, v71, v194
	v_cvt_pk_bf16_f32 v146, v66, v67
	v_cvt_pk_bf16_f32 v147, v68, v69
	ds_read_b64_tr_b16 v[64:65], v201 offset:30720
	ds_read_b64_tr_b16 v[66:67], v201 offset:31232
	v_mfma_f32_32x32x16_bf16 v[98:113], v[170:173], v[134:137], v[98:113]
	v_add_f32_e32 v195, v72, v195
	v_add_f32_e32 v196, v73, v196
	v_add_f32_e32 v50, v74, v50
	v_add_f32_e32 v194, v75, v194
	v_cvt_pk_bf16_f32 v148, v70, v71
	v_cvt_pk_bf16_f32 v149, v72, v73
	ds_read_b64_tr_b16 v[68:69], v201 offset:27648
	ds_read_b64_tr_b16 v[70:71], v201 offset:28160
	v_mfma_f32_32x32x16_bf16 v[114:129], v[166:169], v[130:133], v[114:129]
	v_add_f32_e32 v195, v76, v195
	v_add_f32_e32 v196, v77, v196
	v_add_f32_e32 v50, v78, v50
	v_add_f32_e32 v194, v79, v194
	v_cvt_pk_bf16_f32 v142, v74, v75
	v_cvt_pk_bf16_f32 v143, v76, v77
	ds_read_b64_tr_b16 v[72:73], v201 offset:31744
	ds_read_b64_tr_b16 v[74:75], v201 offset:32256
	v_mfma_f32_32x32x16_bf16 v[98:113], v[162:165], v[130:133], v[98:113]
	v_add_f32_e32 v195, v80, v195
	v_add_f32_e32 v196, v81, v196
	v_cvt_pk_bf16_f32 v144, v78, v79
	v_cvt_pk_bf16_f32 v145, v80, v81
	s_add_i32 m0, s31, s70
	s_nop 0
	global_load_lds_dwordx4 v197, s[98:99]
	s_add_i32 m0, s76, s71
	s_nop 0
	global_load_lds_dwordx4 v197, s[100:101]
	s_add_u32 s98, s98, 0x2000
	s_addc_u32 s99, s99, 0
	s_add_u32 s100, s100, 0x2000
	s_addc_u32 s101, s101, 0
	s_waitcnt lgkmcnt(14)
	v_mfma_f32_32x32x16_bf16 v[2:17], v[158:161], v[52:55], v[2:17]
	v_exp_f32_e32 v114, v114
	v_exp_f32_e32 v115, v115
	v_exp_f32_e32 v116, v116
	v_exp_f32_e32 v117, v117
	s_waitcnt lgkmcnt(12)
	v_mfma_f32_32x32x16_bf16 v[18:33], v[158:161], v[60:63], v[18:33]
	v_exp_f32_e32 v118, v118
	v_exp_f32_e32 v119, v119
	v_exp_f32_e32 v120, v120
	v_exp_f32_e32 v121, v121
	ds_read_b128 v[60:63], v203
	ds_read_b128 v[162:165], v203 offset:512
	s_waitcnt lgkmcnt(12)
	v_mfma_f32_32x32x16_bf16 v[2:17], v[154:157], v[82:85], v[2:17]
	v_exp_f32_e32 v122, v122
	v_exp_f32_e32 v123, v123
	v_exp_f32_e32 v124, v124
	v_exp_f32_e32 v125, v125
	ds_read_b128 v[166:169], v203 offset:2048
	ds_read_b128 v[170:173], v203 offset:2560
	s_waitcnt lgkmcnt(12)
	v_mfma_f32_32x32x16_bf16 v[18:33], v[154:157], v[86:89], v[18:33]
	v_exp_f32_e32 v126, v126
	v_exp_f32_e32 v127, v127
	v_exp_f32_e32 v128, v128
	v_exp_f32_e32 v129, v129
	ds_read_b128 v[174:177], v203 offset:4096
	ds_read_b128 v[178:181], v203 offset:4608
	s_waitcnt lgkmcnt(12)
	v_mfma_f32_32x32x16_bf16 v[2:17], v[146:149], v[90:93], v[2:17]
	v_exp_f32_e32 v98, v98
	v_exp_f32_e32 v99, v99
	v_exp_f32_e32 v100, v100
	v_exp_f32_e32 v101, v101
	ds_read_b128 v[182:185], v203 offset:6144
	ds_read_b128 v[52:55], v203 offset:6656
	s_waitcnt lgkmcnt(12)
	v_mfma_f32_32x32x16_bf16 v[18:33], v[146:149], v[64:67], v[18:33]
	v_exp_f32_e32 v102, v102
	v_exp_f32_e32 v103, v103
	v_exp_f32_e32 v104, v104
	v_exp_f32_e32 v105, v105
	s_waitcnt lgkmcnt(10)
	v_mfma_f32_32x32x16_bf16 v[2:17], v[142:145], v[68:71], v[2:17]
	v_exp_f32_e32 v106, v106
	v_exp_f32_e32 v107, v107
	v_exp_f32_e32 v108, v108
	v_exp_f32_e32 v109, v109
	s_waitcnt lgkmcnt(8)
	v_mfma_f32_32x32x16_bf16 v[18:33], v[142:145], v[72:75], v[18:33]
	v_exp_f32_e32 v110, v110
	v_exp_f32_e32 v111, v111
	v_exp_f32_e32 v112, v112
	v_exp_f32_e32 v113, v113
	s_add_i32 s6, s76, 0x2000
	s_cmpk_lg_i32 s76, 0x4000
	s_cselect_b32 s31, s6, 0
	s_waitcnt vmcnt(2) lgkmcnt(0)
	s_barrier
; #define WAIT_BAR(N) asm volatile("s_waitcnt vmcnt(" #N ") lgkmcnt(0)\n\ts_barrier":::"memory")
;   #define RESC() do{ if(resc){ asm volatile("s_waitcnt lgkmcnt(0)":::"memory"); \
;       _Pragma("unroll") for(int d_=0;d_<2;++d_) _Pragma("unroll") for(int r=0;r<16;++r)o[d_][r]*=wsf[crow(r,hi)]; } }while(0)
;   #define ROT() do{sl_prev=sl_cur;sl_cur=sl_next;sl_next=(sl_next==(NSLOT-1)*SLOTB)?0:sl_next+SLOTB;}while(0)
; template<int THRL> __device__ __forceinline__ void attn_unit(const bf16*Qu,const bf16*__restrict__ Kh,const bf16*__restrict__ Vh,bf16*Ou,const int NT,const float shift,char*shm){
;     ...
;     STEP(pB0,pB1,pA0,pA1,t,true,true,true);     WAIT_BAR(2); RESC(); ROT();
;     STEP(pA0,pA1,pB0,pB1,t+1,true,true,true);   WAIT_BAR(2); RESC(); ROT();
	ds_read_b64_tr_b16 v[186:187], v199 offset:24576
	ds_read_b64_tr_b16 v[188:189], v199 offset:25088
	v_mfma_f32_32x32x16_bf16 v[82:97], v[60:63], v[150:153], v[34:49]
	v_add_f32_e32 v50, v114, v50
	v_add_f32_e32 v194, v115, v194
	v_add_f32_e32 v195, v116, v195
	v_add_f32_e32 v196, v117, v196
	v_add_f32_e32 v50, v118, v50
	v_add_f32_e32 v194, v119, v194
	v_cvt_pk_bf16_f32 v158, v114, v115
	v_cvt_pk_bf16_f32 v159, v116, v117
	ds_read_b64_tr_b16 v[60:61], v199 offset:28672
	ds_read_b64_tr_b16 v[62:63], v199 offset:29184
	v_mfma_f32_32x32x16_bf16 v[66:81], v[162:165], v[150:153], v[34:49]
	v_add_f32_e32 v195, v120, v195
	v_add_f32_e32 v196, v121, v196
	v_add_f32_e32 v50, v122, v50
	v_add_f32_e32 v194, v123, v194
	v_cvt_pk_bf16_f32 v160, v118, v119
	v_cvt_pk_bf16_f32 v161, v120, v121
	ds_read_b64_tr_b16 v[114:115], v199 offset:25600
	ds_read_b64_tr_b16 v[116:117], v199 offset:26112
	v_mfma_f32_32x32x16_bf16 v[82:97], v[166:169], v[138:141], v[82:97]
	v_add_f32_e32 v195, v124, v195
	v_add_f32_e32 v196, v125, v196
	v_add_f32_e32 v50, v126, v50
	v_add_f32_e32 v194, v127, v194
	v_cvt_pk_bf16_f32 v154, v122, v123
	v_cvt_pk_bf16_f32 v155, v124, v125
	ds_read_b64_tr_b16 v[118:119], v199 offset:29696
	ds_read_b64_tr_b16 v[120:121], v199 offset:30208
	v_mfma_f32_32x32x16_bf16 v[66:81], v[170:173], v[138:141], v[66:81]
	v_add_f32_e32 v195, v128, v195
	v_add_f32_e32 v196, v129, v196
	v_add_f32_e32 v50, v98, v50
	v_add_f32_e32 v194, v99, v194
	v_cvt_pk_bf16_f32 v156, v126, v127
	v_cvt_pk_bf16_f32 v157, v128, v129
	ds_read_b64_tr_b16 v[122:123], v199 offset:26624
	ds_read_b64_tr_b16 v[124:125], v199 offset:27136
	v_mfma_f32_32x32x16_bf16 v[82:97], v[174:177], v[134:137], v[82:97]
	v_add_f32_e32 v195, v100, v195
	v_add_f32_e32 v196, v101, v196
	v_add_f32_e32 v50, v102, v50
	v_add_f32_e32 v194, v103, v194
	v_cvt_pk_bf16_f32 v146, v98, v99
	v_cvt_pk_bf16_f32 v147, v100, v101
	ds_read_b64_tr_b16 v[98:99], v199 offset:30720
	ds_read_b64_tr_b16 v[100:101], v199 offset:31232
	v_mfma_f32_32x32x16_bf16 v[66:81], v[178:181], v[134:137], v[66:81]
	v_add_f32_e32 v195, v104, v195
	v_add_f32_e32 v196, v105, v196
	v_add_f32_e32 v50, v106, v50
	v_add_f32_e32 v194, v107, v194
	v_cvt_pk_bf16_f32 v148, v102, v103
	v_cvt_pk_bf16_f32 v149, v104, v105
	ds_read_b64_tr_b16 v[102:103], v199 offset:27648
	ds_read_b64_tr_b16 v[104:105], v199 offset:28160
	v_mfma_f32_32x32x16_bf16 v[82:97], v[182:185], v[130:133], v[82:97]
	v_add_f32_e32 v195, v108, v195
	v_add_f32_e32 v196, v109, v196
	v_add_f32_e32 v50, v110, v50
	v_add_f32_e32 v194, v111, v194
	v_cvt_pk_bf16_f32 v142, v106, v107
	v_cvt_pk_bf16_f32 v143, v108, v109
	ds_read_b64_tr_b16 v[106:107], v199 offset:31744
	ds_read_b64_tr_b16 v[108:109], v199 offset:32256
	v_mfma_f32_32x32x16_bf16 v[66:81], v[52:55], v[130:133], v[66:81]
	v_add_f32_e32 v195, v112, v195
	v_add_f32_e32 v196, v113, v196
	v_cvt_pk_bf16_f32 v144, v110, v111
	v_cvt_pk_bf16_f32 v145, v112, v113
	s_add_i32 m0, s76, s70
	s_nop 0
	global_load_lds_dwordx4 v197, s[98:99]
	s_add_i32 m0, s31, s71
	s_nop 0
	global_load_lds_dwordx4 v197, s[100:101]
	s_add_u32 s98, s98, 0x2000
	s_addc_u32 s99, s99, 0
	s_add_u32 s100, s100, 0x2000
	s_addc_u32 s101, s101, 0
	s_waitcnt lgkmcnt(14)
	v_mfma_f32_32x32x16_bf16 v[2:17], v[158:161], v[186:189], v[2:17]
	v_exp_f32_e32 v82, v82
	v_exp_f32_e32 v83, v83
	v_exp_f32_e32 v84, v84
	v_exp_f32_e32 v85, v85
	s_waitcnt lgkmcnt(12)
	v_mfma_f32_32x32x16_bf16 v[18:33], v[158:161], v[60:63], v[18:33]
	v_exp_f32_e32 v86, v86
	v_exp_f32_e32 v87, v87
	v_exp_f32_e32 v88, v88
	v_exp_f32_e32 v89, v89
	ds_read_b128 v[190:193], v204
	ds_read_b128 v[186:189], v204 offset:512
	s_waitcnt lgkmcnt(12)
	v_mfma_f32_32x32x16_bf16 v[2:17], v[154:157], v[114:117], v[2:17]
	v_exp_f32_e32 v90, v90
	v_exp_f32_e32 v91, v91
	v_exp_f32_e32 v92, v92
	v_exp_f32_e32 v93, v93
	ds_read_b128 v[182:185], v204 offset:2048
	ds_read_b128 v[178:181], v204 offset:2560
	s_waitcnt lgkmcnt(12)
	v_mfma_f32_32x32x16_bf16 v[18:33], v[154:157], v[118:121], v[18:33]
	v_exp_f32_e32 v94, v94
	v_exp_f32_e32 v95, v95
	v_exp_f32_e32 v96, v96
	v_exp_f32_e32 v97, v97
	ds_read_b128 v[174:177], v204 offset:4096
	ds_read_b128 v[170:173], v204 offset:4608
	s_waitcnt lgkmcnt(12)
	v_mfma_f32_32x32x16_bf16 v[2:17], v[146:149], v[122:125], v[2:17]
	v_exp_f32_e32 v66, v66
	v_exp_f32_e32 v67, v67
	v_exp_f32_e32 v68, v68
	v_exp_f32_e32 v69, v69
	ds_read_b128 v[166:169], v204 offset:6144
	ds_read_b128 v[162:165], v204 offset:6656
	s_waitcnt lgkmcnt(12)
	v_mfma_f32_32x32x16_bf16 v[18:33], v[146:149], v[98:101], v[18:33]
	v_exp_f32_e32 v70, v70
	v_exp_f32_e32 v71, v71
	v_exp_f32_e32 v72, v72
	v_exp_f32_e32 v73, v73
	s_waitcnt lgkmcnt(10)
	v_mfma_f32_32x32x16_bf16 v[2:17], v[142:145], v[102:105], v[2:17]
	v_exp_f32_e32 v74, v74
	v_exp_f32_e32 v75, v75
	v_exp_f32_e32 v76, v76
	v_exp_f32_e32 v77, v77
	s_waitcnt lgkmcnt(8)
	v_mfma_f32_32x32x16_bf16 v[18:33], v[142:145], v[106:109], v[18:33]
	v_exp_f32_e32 v78, v78
	v_exp_f32_e32 v79, v79
	v_exp_f32_e32 v80, v80
	v_exp_f32_e32 v81, v81
	s_add_i32 s6, s31, 0x2000
	s_cmpk_lg_i32 s31, 0x4000
	s_mov_b32 s24, s76
	s_cselect_b32 s76, s6, 0
	s_add_i32 s26, s26, 2
	s_cmp_gt_i32 s26, s91
	s_cbranch_scc1 .Lattn_exit
	s_waitcnt vmcnt(2) lgkmcnt(0)
	s_barrier
.Lattn_cpC:
	ds_read_b64_tr_b16 v[52:53], v200 offset:24576
	ds_read_b64_tr_b16 v[54:55], v200 offset:25088
	v_mfma_f32_32x32x16_bf16 v[114:129], v[190:193], v[150:153], v[34:49]
	v_add_f32_e32 v50, v82, v50
	v_add_f32_e32 v194, v83, v194
	v_add_f32_e32 v195, v84, v195
	v_add_f32_e32 v196, v85, v196
	v_add_f32_e32 v50, v86, v50
	v_add_f32_e32 v194, v87, v194
	v_cvt_pk_bf16_f32 v158, v82, v83
	v_cvt_pk_bf16_f32 v159, v84, v85
	ds_read_b64_tr_b16 v[60:61], v200 offset:28672
	ds_read_b64_tr_b16 v[62:63], v200 offset:29184
	v_mfma_f32_32x32x16_bf16 v[98:113], v[186:189], v[150:153], v[34:49]
	v_add_f32_e32 v195, v88, v195
	v_add_f32_e32 v196, v89, v196
	v_add_f32_e32 v50, v90, v50
	v_add_f32_e32 v194, v91, v194
	v_cvt_pk_bf16_f32 v160, v86, v87
	v_cvt_pk_bf16_f32 v161, v88, v89
	ds_read_b64_tr_b16 v[82:83], v200 offset:25600
	ds_read_b64_tr_b16 v[84:85], v200 offset:26112
	v_mfma_f32_32x32x16_bf16 v[114:129], v[182:185], v[138:141], v[114:129]
	v_add_f32_e32 v195, v92, v195
	v_add_f32_e32 v196, v93, v196
	v_add_f32_e32 v50, v94, v50
	v_add_f32_e32 v194, v95, v194
	v_cvt_pk_bf16_f32 v154, v90, v91
	v_cvt_pk_bf16_f32 v155, v92, v93
	ds_read_b64_tr_b16 v[86:87], v200 offset:29696
	ds_read_b64_tr_b16 v[88:89], v200 offset:30208
	v_mfma_f32_32x32x16_bf16 v[98:113], v[178:181], v[138:141], v[98:113]
	v_add_f32_e32 v195, v96, v195
	v_add_f32_e32 v196, v97, v196
	v_add_f32_e32 v50, v66, v50
	v_add_f32_e32 v194, v67, v194
	v_cvt_pk_bf16_f32 v156, v94, v95
	v_cvt_pk_bf16_f32 v157, v96, v97
	ds_read_b64_tr_b16 v[90:91], v200 offset:26624
	ds_read_b64_tr_b16 v[92:93], v200 offset:27136
	v_mfma_f32_32x32x16_bf16 v[114:129], v[174:177], v[134:137], v[114:129]
	v_add_f32_e32 v195, v68, v195
	v_add_f32_e32 v196, v69, v196
	v_add_f32_e32 v50, v70, v50
	v_add_f32_e32 v194, v71, v194
	v_cvt_pk_bf16_f32 v146, v66, v67
	v_cvt_pk_bf16_f32 v147, v68, v69
	ds_read_b64_tr_b16 v[64:65], v200 offset:30720
	ds_read_b64_tr_b16 v[66:67], v200 offset:31232
	v_mfma_f32_32x32x16_bf16 v[98:113], v[170:173], v[134:137], v[98:113]
	v_add_f32_e32 v195, v72, v195
	v_add_f32_e32 v196, v73, v196
	v_add_f32_e32 v50, v74, v50
	v_add_f32_e32 v194, v75, v194
	v_cvt_pk_bf16_f32 v148, v70, v71
	v_cvt_pk_bf16_f32 v149, v72, v73
	ds_read_b64_tr_b16 v[68:69], v200 offset:27648
	ds_read_b64_tr_b16 v[70:71], v200 offset:28160
	v_mfma_f32_32x32x16_bf16 v[114:129], v[166:169], v[130:133], v[114:129]
	v_add_f32_e32 v195, v76, v195
	v_add_f32_e32 v196, v77, v196
	v_add_f32_e32 v50, v78, v50
	v_add_f32_e32 v194, v79, v194
	v_cvt_pk_bf16_f32 v142, v74, v75
	v_cvt_pk_bf16_f32 v143, v76, v77
	ds_read_b64_tr_b16 v[72:73], v200 offset:31744
	ds_read_b64_tr_b16 v[74:75], v200 offset:32256
	v_mfma_f32_32x32x16_bf16 v[98:113], v[162:165], v[130:133], v[98:113]
	v_add_f32_e32 v195, v80, v195
	v_add_f32_e32 v196, v81, v196
	v_cvt_pk_bf16_f32 v144, v78, v79
	v_cvt_pk_bf16_f32 v145, v80, v81
	s_add_i32 m0, s31, s70
	s_nop 0
	global_load_lds_dwordx4 v197, s[98:99]
	s_add_i32 m0, s76, s71
	s_nop 0
	global_load_lds_dwordx4 v197, s[100:101]
	s_add_u32 s98, s98, 0x2000
	s_addc_u32 s99, s99, 0
	s_add_u32 s100, s100, 0x2000
	s_addc_u32 s101, s101, 0
	s_waitcnt lgkmcnt(14)
	v_mfma_f32_32x32x16_bf16 v[2:17], v[158:161], v[52:55], v[2:17]
	v_exp_f32_e32 v114, v114
	v_exp_f32_e32 v115, v115
	v_exp_f32_e32 v116, v116
	v_exp_f32_e32 v117, v117
	s_waitcnt lgkmcnt(12)
	v_mfma_f32_32x32x16_bf16 v[18:33], v[158:161], v[60:63], v[18:33]
	v_exp_f32_e32 v118, v118
	v_exp_f32_e32 v119, v119
	v_exp_f32_e32 v120, v120
	v_exp_f32_e32 v121, v121
	ds_read_b128 v[60:63], v202
	ds_read_b128 v[162:165], v202 offset:512
	s_waitcnt lgkmcnt(12)
	v_mfma_f32_32x32x16_bf16 v[2:17], v[154:157], v[82:85], v[2:17]
	v_exp_f32_e32 v122, v122
	v_exp_f32_e32 v123, v123
	v_exp_f32_e32 v124, v124
	v_exp_f32_e32 v125, v125
	ds_read_b128 v[166:169], v202 offset:2048
	ds_read_b128 v[170:173], v202 offset:2560
	s_waitcnt lgkmcnt(12)
	v_mfma_f32_32x32x16_bf16 v[18:33], v[154:157], v[86:89], v[18:33]
	v_exp_f32_e32 v126, v126
	v_exp_f32_e32 v127, v127
	v_exp_f32_e32 v128, v128
	v_exp_f32_e32 v129, v129
	ds_read_b128 v[174:177], v202 offset:4096
	ds_read_b128 v[178:181], v202 offset:4608
	s_waitcnt lgkmcnt(12)
	v_mfma_f32_32x32x16_bf16 v[2:17], v[146:149], v[90:93], v[2:17]
	v_exp_f32_e32 v98, v98
	v_exp_f32_e32 v99, v99
	v_exp_f32_e32 v100, v100
	v_exp_f32_e32 v101, v101
	ds_read_b128 v[182:185], v202 offset:6144
	ds_read_b128 v[52:55], v202 offset:6656
	s_waitcnt lgkmcnt(12)
	v_mfma_f32_32x32x16_bf16 v[18:33], v[146:149], v[64:67], v[18:33]
	v_exp_f32_e32 v102, v102
	v_exp_f32_e32 v103, v103
	v_exp_f32_e32 v104, v104
	v_exp_f32_e32 v105, v105
	s_waitcnt lgkmcnt(10)
	v_mfma_f32_32x32x16_bf16 v[2:17], v[142:145], v[68:71], v[2:17]
	v_exp_f32_e32 v106, v106
	v_exp_f32_e32 v107, v107
	v_exp_f32_e32 v108, v108
	v_exp_f32_e32 v109, v109
	s_waitcnt lgkmcnt(8)
	v_mfma_f32_32x32x16_bf16 v[18:33], v[142:145], v[72:75], v[18:33]
	v_exp_f32_e32 v110, v110
	v_exp_f32_e32 v111, v111
	v_exp_f32_e32 v112, v112
	v_exp_f32_e32 v113, v113
	s_add_i32 s6, s76, 0x2000
	s_cmpk_lg_i32 s76, 0x4000
	s_cselect_b32 s31, s6, 0
	s_waitcnt vmcnt(2) lgkmcnt(0)
	s_barrier
; #define WAIT_BAR(N) asm volatile("s_waitcnt vmcnt(" #N ") lgkmcnt(0)\n\ts_barrier":::"memory")
;   #define RESC() do{ if(resc){ asm volatile("s_waitcnt lgkmcnt(0)":::"memory"); \
;       _Pragma("unroll") for(int d_=0;d_<2;++d_) _Pragma("unroll") for(int r=0;r<16;++r)o[d_][r]*=wsf[crow(r,hi)]; } }while(0)
;   #define ROT() do{sl_prev=sl_cur;sl_cur=sl_next;sl_next=(sl_next==(NSLOT-1)*SLOTB)?0:sl_next+SLOTB;}while(0)
; template<int THRL> __device__ __forceinline__ void attn_unit(const bf16*Qu,const bf16*__restrict__ Kh,const bf16*__restrict__ Vh,bf16*Ou,const int NT,const float shift,char*shm){
;     ...
;   for(;t+5<NT;t+=2){
;     STEP(pB0,pB1,pA0,pA1,t,true,true,true);     WAIT_BAR(2); RESC(); ROT();
;     STEP(pA0,pA1,pB0,pB1,t+1,true,true,true);   WAIT_BAR(2); RESC(); ROT();
;   }
	ds_read_b64_tr_b16 v[186:187], v201 offset:24576
	ds_read_b64_tr_b16 v[188:189], v201 offset:25088
	v_mfma_f32_32x32x16_bf16 v[82:97], v[60:63], v[150:153], v[34:49]
	v_add_f32_e32 v50, v114, v50
	v_add_f32_e32 v194, v115, v194
	v_add_f32_e32 v195, v116, v195
	v_add_f32_e32 v196, v117, v196
	v_add_f32_e32 v50, v118, v50
	v_add_f32_e32 v194, v119, v194
	v_cvt_pk_bf16_f32 v158, v114, v115
	v_cvt_pk_bf16_f32 v159, v116, v117
	ds_read_b64_tr_b16 v[60:61], v201 offset:28672
	ds_read_b64_tr_b16 v[62:63], v201 offset:29184
	v_mfma_f32_32x32x16_bf16 v[66:81], v[162:165], v[150:153], v[34:49]
	v_add_f32_e32 v195, v120, v195
	v_add_f32_e32 v196, v121, v196
	v_add_f32_e32 v50, v122, v50
	v_add_f32_e32 v194, v123, v194
	v_cvt_pk_bf16_f32 v160, v118, v119
	v_cvt_pk_bf16_f32 v161, v120, v121
	ds_read_b64_tr_b16 v[114:115], v201 offset:25600
	ds_read_b64_tr_b16 v[116:117], v201 offset:26112
	v_mfma_f32_32x32x16_bf16 v[82:97], v[166:169], v[138:141], v[82:97]
	v_add_f32_e32 v195, v124, v195
	v_add_f32_e32 v196, v125, v196
	v_add_f32_e32 v50, v126, v50
	v_add_f32_e32 v194, v127, v194
	v_cvt_pk_bf16_f32 v154, v122, v123
	v_cvt_pk_bf16_f32 v155, v124, v125
	ds_read_b64_tr_b16 v[118:119], v201 offset:29696
	ds_read_b64_tr_b16 v[120:121], v201 offset:30208
	v_mfma_f32_32x32x16_bf16 v[66:81], v[170:173], v[138:141], v[66:81]
	v_add_f32_e32 v195, v128, v195
	v_add_f32_e32 v196, v129, v196
	v_add_f32_e32 v50, v98, v50
	v_add_f32_e32 v194, v99, v194
	v_cvt_pk_bf16_f32 v156, v126, v127
	v_cvt_pk_bf16_f32 v157, v128, v129
	ds_read_b64_tr_b16 v[122:123], v201 offset:26624
	ds_read_b64_tr_b16 v[124:125], v201 offset:27136
	v_mfma_f32_32x32x16_bf16 v[82:97], v[174:177], v[134:137], v[82:97]
	v_add_f32_e32 v195, v100, v195
	v_add_f32_e32 v196, v101, v196
	v_add_f32_e32 v50, v102, v50
	v_add_f32_e32 v194, v103, v194
	v_cvt_pk_bf16_f32 v146, v98, v99
	v_cvt_pk_bf16_f32 v147, v100, v101
	ds_read_b64_tr_b16 v[98:99], v201 offset:30720
	ds_read_b64_tr_b16 v[100:101], v201 offset:31232
	v_mfma_f32_32x32x16_bf16 v[66:81], v[178:181], v[134:137], v[66:81]
	v_add_f32_e32 v195, v104, v195
	v_add_f32_e32 v196, v105, v196
	v_add_f32_e32 v50, v106, v50
	v_add_f32_e32 v194, v107, v194
	v_cvt_pk_bf16_f32 v148, v102, v103
	v_cvt_pk_bf16_f32 v149, v104, v105
	ds_read_b64_tr_b16 v[102:103], v201 offset:27648
	ds_read_b64_tr_b16 v[104:105], v201 offset:28160
	v_mfma_f32_32x32x16_bf16 v[82:97], v[182:185], v[130:133], v[82:97]
	v_add_f32_e32 v195, v108, v195
	v_add_f32_e32 v196, v109, v196
	v_add_f32_e32 v50, v110, v50
	v_add_f32_e32 v194, v111, v194
	v_cvt_pk_bf16_f32 v142, v106, v107
	v_cvt_pk_bf16_f32 v143, v108, v109
	ds_read_b64_tr_b16 v[106:107], v201 offset:31744
	ds_read_b64_tr_b16 v[108:109], v201 offset:32256
	v_mfma_f32_32x32x16_bf16 v[66:81], v[52:55], v[130:133], v[66:81]
	v_add_f32_e32 v195, v112, v195
	v_add_f32_e32 v196, v113, v196
	v_cvt_pk_bf16_f32 v144, v110, v111
	v_cvt_pk_bf16_f32 v145, v112, v113
	s_add_i32 m0, s76, s70
	s_nop 0
	global_load_lds_dwordx4 v197, s[98:99]
	s_add_i32 m0, s31, s71
	s_nop 0
	global_load_lds_dwordx4 v197, s[100:101]
	s_add_u32 s98, s98, 0x2000
	s_addc_u32 s99, s99, 0
	s_add_u32 s100, s100, 0x2000
	s_addc_u32 s101, s101, 0
	s_waitcnt lgkmcnt(14)
	v_mfma_f32_32x32x16_bf16 v[2:17], v[158:161], v[186:189], v[2:17]
	v_exp_f32_e32 v82, v82
	v_exp_f32_e32 v83, v83
	v_exp_f32_e32 v84, v84
	v_exp_f32_e32 v85, v85
	s_waitcnt lgkmcnt(12)
	v_mfma_f32_32x32x16_bf16 v[18:33], v[158:161], v[60:63], v[18:33]
	v_exp_f32_e32 v86, v86
	v_exp_f32_e32 v87, v87
	v_exp_f32_e32 v88, v88
	v_exp_f32_e32 v89, v89
	ds_read_b128 v[190:193], v203
	ds_read_b128 v[186:189], v203 offset:512
	s_waitcnt lgkmcnt(12)
	v_mfma_f32_32x32x16_bf16 v[2:17], v[154:157], v[114:117], v[2:17]
	v_exp_f32_e32 v90, v90
	v_exp_f32_e32 v91, v91
	v_exp_f32_e32 v92, v92
	v_exp_f32_e32 v93, v93
	ds_read_b128 v[182:185], v203 offset:2048
	ds_read_b128 v[178:181], v203 offset:2560
	s_waitcnt lgkmcnt(12)
	v_mfma_f32_32x32x16_bf16 v[18:33], v[154:157], v[118:121], v[18:33]
	v_exp_f32_e32 v94, v94
	v_exp_f32_e32 v95, v95
	v_exp_f32_e32 v96, v96
	v_exp_f32_e32 v97, v97
	ds_read_b128 v[174:177], v203 offset:4096
	ds_read_b128 v[170:173], v203 offset:4608
	s_waitcnt lgkmcnt(12)
	v_mfma_f32_32x32x16_bf16 v[2:17], v[146:149], v[122:125], v[2:17]
	v_exp_f32_e32 v66, v66
	v_exp_f32_e32 v67, v67
	v_exp_f32_e32 v68, v68
	v_exp_f32_e32 v69, v69
	ds_read_b128 v[166:169], v203 offset:6144
	ds_read_b128 v[162:165], v203 offset:6656
	s_waitcnt lgkmcnt(12)
	v_mfma_f32_32x32x16_bf16 v[18:33], v[146:149], v[98:101], v[18:33]
	v_exp_f32_e32 v70, v70
	v_exp_f32_e32 v71, v71
	v_exp_f32_e32 v72, v72
	v_exp_f32_e32 v73, v73
	s_waitcnt lgkmcnt(10)
	v_mfma_f32_32x32x16_bf16 v[2:17], v[142:145], v[102:105], v[2:17]
	v_exp_f32_e32 v74, v74
	v_exp_f32_e32 v75, v75
	v_exp_f32_e32 v76, v76
	v_exp_f32_e32 v77, v77
	s_waitcnt lgkmcnt(8)
	v_mfma_f32_32x32x16_bf16 v[18:33], v[142:145], v[106:109], v[18:33]
	v_exp_f32_e32 v78, v78
	v_exp_f32_e32 v79, v79
	v_exp_f32_e32 v80, v80
	v_exp_f32_e32 v81, v81
	s_add_i32 s6, s31, 0x2000
	s_cmpk_lg_i32 s31, 0x4000
	s_mov_b32 s24, s76
	s_cselect_b32 s76, s6, 0
	s_add_i32 s26, s26, 2
	s_cmp_gt_i32 s26, s91
	s_cbranch_scc0 .Lattn_rot
